# P3/P8 epilogue residual loads with contiguous lane order + ds_bpermute (same address correction as the stores)
# baseline (speedup 1.0000x reference)
.LBB0_726:
	v_lshl_or_b32 v130, s50, 8, v191
	v_and_b32_e32 v243, 63, v204
	v_lshrrev_b32_e32 v244, 2, v243
	v_and_b32_e32 v240, 3, v243
	v_lshlrev_b32_e32 v242, 4, v240
	v_add_u32_e32 v242, v242, v244
	v_lshlrev_b32_e32 v242, 2, v242
	v_and_b32_e32 v241, 15, v243
	v_sub_u32_e32 v244, v244, v241
	v_lshlrev_b32_e32 v244, 11, v244
	v_bfe_u32 v241, v243, 4, 2
	v_sub_u32_e32 v240, v240, v241
	v_lshlrev_b32_e32 v240, 4, v240
	v_add_u32_e32 v240, v244, v240
	v_ashrrev_i32_e32 v241, 31, v240
	v_lshrrev_b32_e32 v244, 4, v243
	v_lshlrev_b32_e32 v244, 2, v244
	v_and_b32_e32 v243, 15, v243
	v_lshl_or_b32 v244, v243, 4, v244
	v_lshl_add_u32 v168, s51, 8, v176
	v_ashrrev_i32_e32 v131, 31, v130
	v_lshlrev_b64 v[170:171], 1, v[130:131]
	v_or_b32_e32 v130, 16, v168
	v_ashrrev_i32_e32 v131, 31, v130
	v_lshlrev_b64 v[130:131], 11, v[130:131]
	v_lshl_add_u64 v[130:131], s[64:65], 0, v[130:131]
	v_lshl_add_u64 v[186:187], v[130:131], 0, v[170:171]
	v_or_b32_e32 v130, 32, v168
	v_ashrrev_i32_e32 v131, 31, v130
	v_lshlrev_b64 v[130:131], 11, v[130:131]
	v_lshl_add_u64 v[130:131], s[64:65], 0, v[130:131]
	v_lshl_add_u64 v[174:175], v[130:131], 0, v[170:171]
	v_or_b32_e32 v130, 48, v168
	v_ashrrev_i32_e32 v169, 31, v168
	v_ashrrev_i32_e32 v131, 31, v130
	v_lshlrev_b64 v[132:133], 11, v[168:169]
	v_lshlrev_b64 v[130:131], 11, v[130:131]
	v_lshl_add_u64 v[132:133], s[64:65], 0, v[132:133]
	v_lshl_add_u64 v[130:131], s[64:65], 0, v[130:131]
	v_lshl_add_u64 v[188:189], v[132:133], 0, v[170:171]
	v_lshl_add_u64 v[172:173], v[130:131], 0, v[170:171]
	v_lshl_add_u64 v[188:189], v[188:189], 0, v[240:241]
	global_load_dwordx4 v[194:197], v[188:189], off
	global_load_dwordx4 v[154:157], v[188:189], off offset:256
	v_lshl_add_u64 v[186:187], v[186:187], 0, v[240:241]
	global_load_dwordx4 v[150:153], v[186:187], off
	global_load_dwordx4 v[146:149], v[186:187], off offset:256
	v_lshl_add_u64 v[174:175], v[174:175], 0, v[240:241]
	global_load_dwordx4 v[142:145], v[174:175], off
	global_load_dwordx4 v[138:141], v[174:175], off offset:256
	v_lshl_add_u64 v[172:173], v[172:173], 0, v[240:241]
	global_load_dwordx4 v[134:137], v[172:173], off
	global_load_dwordx4 v[130:133], v[172:173], off offset:256
	s_waitcnt vmcnt(0)
	ds_bpermute_b32 v194, v244, v194
	ds_bpermute_b32 v195, v244, v195
	ds_bpermute_b32 v196, v244, v196
	ds_bpermute_b32 v197, v244, v197
	ds_bpermute_b32 v154, v244, v154
	ds_bpermute_b32 v155, v244, v155
	ds_bpermute_b32 v156, v244, v156
	ds_bpermute_b32 v157, v244, v157
	ds_bpermute_b32 v150, v244, v150
	ds_bpermute_b32 v151, v244, v151
	ds_bpermute_b32 v152, v244, v152
	ds_bpermute_b32 v153, v244, v153
	ds_bpermute_b32 v146, v244, v146
	ds_bpermute_b32 v147, v244, v147
	ds_bpermute_b32 v148, v244, v148
	ds_bpermute_b32 v149, v244, v149
	s_waitcnt lgkmcnt(0)
	ds_bpermute_b32 v142, v244, v142
	ds_bpermute_b32 v143, v244, v143
	ds_bpermute_b32 v144, v244, v144
	ds_bpermute_b32 v145, v244, v145
	ds_bpermute_b32 v138, v244, v138
	ds_bpermute_b32 v139, v244, v139
	ds_bpermute_b32 v140, v244, v140
	ds_bpermute_b32 v141, v244, v141
	ds_bpermute_b32 v134, v244, v134
	ds_bpermute_b32 v135, v244, v135
	ds_bpermute_b32 v136, v244, v136
	ds_bpermute_b32 v137, v244, v137
	ds_bpermute_b32 v130, v244, v130
	ds_bpermute_b32 v131, v244, v131
	ds_bpermute_b32 v132, v244, v132
	ds_bpermute_b32 v133, v244, v133
	s_waitcnt lgkmcnt(0)
	v_lshlrev_b32_e32 v198, 16, v194
	v_and_b32_e32 v199, 0xffff0000, v194
	v_lshlrev_b32_e32 v194, 16, v195
	v_and_b32_e32 v195, 0xffff0000, v195
	v_pk_add_f32 v[128:129], v[128:129], v[194:195]
	v_lshlrev_b32_e32 v194, 16, v196
	v_and_b32_e32 v195, 0xffff0000, v196
	v_lshlrev_b32_e32 v196, 16, v197
	v_and_b32_e32 v197, 0xffff0000, v197
	v_cndmask_b32_e64 v193, 0, 1, s[94:95]
	v_pk_add_f32 v[126:127], v[126:127], v[198:199]
	v_pk_add_f32 v[124:125], v[124:125], v[196:197]
	v_cmp_ne_u32_e64 s[42:43], 1, v193
	s_andn2_b64 vcc, exec, s[94:95]
	v_pk_add_f32 v[122:123], v[122:123], v[194:195]
	s_cbranch_vccnz .LBB0_728
	v_cvt_pk_bf16_f32 v194, v126, v127
	v_cvt_pk_bf16_f32 v195, v128, v129
	v_cvt_pk_bf16_f32 v196, v122, v123
	v_cvt_pk_bf16_f32 v197, v124, v125
	ds_bpermute_b32 v194, v242, v194
	ds_bpermute_b32 v195, v242, v195
	ds_bpermute_b32 v196, v242, v196
	ds_bpermute_b32 v197, v242, v197
	s_waitcnt lgkmcnt(0)
	global_store_dwordx4 v[188:189], v[194:197], off

.LBB0_730:
	v_mul_f32_e32 v127, v127, v127
	v_mul_f32_e32 v123, v123, v123
	v_mul_f32_e32 v119, v119, v119
	v_mul_f32_e32 v115, v115, v115
	v_fmac_f32_e32 v127, v126, v126
	v_mul_f32_e32 v126, v129, v129
	v_fmac_f32_e32 v123, v122, v122
	v_mul_f32_e32 v122, v125, v125
	v_fmac_f32_e32 v119, v118, v118
	v_mul_f32_e32 v118, v121, v121
	v_fmac_f32_e32 v115, v114, v114
	v_mul_f32_e32 v114, v117, v117
	v_fmac_f32_e32 v126, v128, v128
	v_fmac_f32_e32 v122, v124, v124
	v_fmac_f32_e32 v118, v120, v120
	v_fmac_f32_e32 v114, v116, v116
	v_add_f32_e32 v126, v127, v126
	v_add_f32_e32 v122, v123, v122
	v_cmp_lt_i32_e32 vcc, v210, v206
	v_add_f32_e32 v118, v119, v118
	v_add_f32_e32 v114, v115, v114
	v_add_f32_e32 v123, v126, v122
	v_cndmask_b32_e32 v122, v205, v210, vcc
	v_add_f32_e32 v114, v118, v114
	v_lshlrev_b32_e32 v122, 2, v122
	v_add_f32_e32 v114, v123, v114
	ds_bpermute_b32 v115, v122, v114
	v_cmp_lt_i32_e32 vcc, v209, v206
	v_lshlrev_b32_e32 v118, 16, v150
	v_and_b32_e32 v119, 0xffff0000, v150
	v_cndmask_b32_e32 v116, v205, v209, vcc
	v_lshlrev_b32_e32 v116, 2, v116
	s_waitcnt lgkmcnt(0)
	v_add_f32_e32 v114, v114, v115
	ds_bpermute_b32 v115, v116, v114
	v_lshlrev_b32_e32 v120, 16, v151
	v_and_b32_e32 v121, 0xffff0000, v151
	v_pk_add_f32 v[112:113], v[112:113], v[120:121]
	v_pk_add_f32 v[110:111], v[110:111], v[118:119]
	v_lshlrev_b32_e32 v118, 16, v152
	v_and_b32_e32 v119, 0xffff0000, v152
	v_lshlrev_b32_e32 v120, 16, v153
	v_and_b32_e32 v121, 0xffff0000, v153
	v_pk_add_f32 v[108:109], v[108:109], v[120:121]
	s_and_b64 vcc, exec, s[42:43]
	v_pk_add_f32 v[106:107], v[106:107], v[118:119]
	s_cbranch_vccnz .LBB0_732
	v_cvt_pk_bf16_f32 v118, v110, v111
	v_cvt_pk_bf16_f32 v119, v112, v113
	v_cvt_pk_bf16_f32 v120, v106, v107
	v_cvt_pk_bf16_f32 v121, v108, v109
	ds_bpermute_b32 v118, v242, v118
	ds_bpermute_b32 v119, v242, v119
	ds_bpermute_b32 v120, v242, v120
	ds_bpermute_b32 v121, v242, v121
	s_waitcnt lgkmcnt(0)
	global_store_dwordx4 v[186:187], v[118:121], off

.LBB0_734:
	v_mul_f32_e32 v111, v111, v111
	v_mul_f32_e32 v107, v107, v107
	v_mul_f32_e32 v103, v103, v103
	v_mul_f32_e32 v99, v99, v99
	v_fmac_f32_e32 v111, v110, v110
	v_mul_f32_e32 v110, v113, v113
	v_fmac_f32_e32 v107, v106, v106
	v_mul_f32_e32 v106, v109, v109
	v_fmac_f32_e32 v103, v102, v102
	v_mul_f32_e32 v102, v105, v105
	v_fmac_f32_e32 v99, v98, v98
	v_mul_f32_e32 v98, v101, v101
	v_fmac_f32_e32 v110, v112, v112
	v_fmac_f32_e32 v106, v108, v108
	v_fmac_f32_e32 v102, v104, v104
	v_fmac_f32_e32 v98, v100, v100
	v_add_f32_e32 v110, v111, v110
	v_add_f32_e32 v106, v107, v106
	v_add_f32_e32 v102, v103, v102
	v_add_f32_e32 v98, v99, v98
	v_add_f32_e32 v106, v110, v106
	v_add_f32_e32 v98, v102, v98
	v_add_f32_e32 v98, v106, v98
	ds_bpermute_b32 v99, v122, v98
	v_lshlrev_b32_e32 v100, 16, v143
	v_and_b32_e32 v101, 0xffff0000, v143
	v_pk_add_f32 v[96:97], v[96:97], v[100:101]
	v_lshlrev_b32_e32 v100, 16, v145
	s_waitcnt lgkmcnt(0)
	v_add_f32_e32 v102, v98, v99
	ds_bpermute_b32 v103, v116, v102
	v_lshlrev_b32_e32 v98, 16, v142
	v_and_b32_e32 v99, 0xffff0000, v142
	v_pk_add_f32 v[94:95], v[94:95], v[98:99]
	v_lshlrev_b32_e32 v98, 16, v144
	v_and_b32_e32 v99, 0xffff0000, v144
	v_and_b32_e32 v101, 0xffff0000, v145
	v_pk_add_f32 v[92:93], v[92:93], v[100:101]
	s_and_b64 vcc, exec, s[42:43]
	v_pk_add_f32 v[90:91], v[90:91], v[98:99]
	s_cbranch_vccnz .LBB0_736
	v_cvt_pk_bf16_f32 v98, v94, v95
	v_cvt_pk_bf16_f32 v99, v96, v97
	v_cvt_pk_bf16_f32 v100, v90, v91
	v_cvt_pk_bf16_f32 v101, v92, v93
	ds_bpermute_b32 v98, v242, v98
	ds_bpermute_b32 v99, v242, v99
	ds_bpermute_b32 v100, v242, v100
	ds_bpermute_b32 v101, v242, v101
	s_waitcnt lgkmcnt(0)
	global_store_dwordx4 v[174:175], v[98:101], off

.LBB0_738:
	v_mul_f32_e32 v95, v95, v95
	v_mul_f32_e32 v91, v91, v91
	v_mul_f32_e32 v87, v87, v87
	v_mul_f32_e32 v83, v83, v83
	v_fmac_f32_e32 v95, v94, v94
	v_mul_f32_e32 v94, v97, v97
	v_fmac_f32_e32 v91, v90, v90
	v_mul_f32_e32 v90, v93, v93
	v_fmac_f32_e32 v87, v86, v86
	v_mul_f32_e32 v86, v89, v89
	v_fmac_f32_e32 v83, v82, v82
	v_mul_f32_e32 v82, v85, v85
	v_fmac_f32_e32 v94, v96, v96
	v_fmac_f32_e32 v90, v92, v92
	v_fmac_f32_e32 v86, v88, v88
	v_fmac_f32_e32 v82, v84, v84
	v_add_f32_e32 v94, v95, v94
	v_add_f32_e32 v90, v91, v90
	v_add_f32_e32 v86, v87, v86
	v_add_f32_e32 v82, v83, v82
	v_add_f32_e32 v90, v94, v90
	v_add_f32_e32 v82, v86, v82
	v_add_f32_e32 v82, v90, v82
	ds_bpermute_b32 v83, v122, v82
	v_lshlrev_b32_e32 v84, 16, v135
	v_and_b32_e32 v85, 0xffff0000, v135
	v_pk_add_f32 v[80:81], v[80:81], v[84:85]
	v_lshlrev_b32_e32 v84, 16, v137
	s_waitcnt lgkmcnt(0)
	v_add_f32_e32 v104, v82, v83
	ds_bpermute_b32 v105, v116, v104
	v_lshlrev_b32_e32 v82, 16, v134
	v_and_b32_e32 v83, 0xffff0000, v134
	v_pk_add_f32 v[78:79], v[78:79], v[82:83]
	v_lshlrev_b32_e32 v82, 16, v136
	v_and_b32_e32 v83, 0xffff0000, v136
	v_and_b32_e32 v85, 0xffff0000, v137
	v_pk_add_f32 v[76:77], v[76:77], v[84:85]
	s_and_b64 vcc, exec, s[42:43]
	v_pk_add_f32 v[74:75], v[74:75], v[82:83]
	s_cbranch_vccnz .LBB0_740
	v_cvt_pk_bf16_f32 v82, v78, v79
	v_cvt_pk_bf16_f32 v83, v80, v81
	v_cvt_pk_bf16_f32 v84, v74, v75
	v_cvt_pk_bf16_f32 v85, v76, v77
	ds_bpermute_b32 v82, v242, v82
	ds_bpermute_b32 v83, v242, v83
	ds_bpermute_b32 v84, v242, v84
	ds_bpermute_b32 v85, v242, v85
	s_waitcnt lgkmcnt(0)
	global_store_dwordx4 v[172:173], v[82:85], off

.LBB0_742:
	v_mul_f32_e32 v79, v79, v79
	v_mul_f32_e32 v75, v75, v75
	v_mul_f32_e32 v71, v71, v71
	v_mul_f32_e32 v67, v67, v67
	v_fmac_f32_e32 v79, v78, v78
	v_mul_f32_e32 v78, v81, v81
	v_fmac_f32_e32 v75, v74, v74
	v_mul_f32_e32 v74, v77, v77
	v_fmac_f32_e32 v71, v70, v70
	v_mul_f32_e32 v70, v73, v73
	v_fmac_f32_e32 v67, v66, v66
	v_mul_f32_e32 v66, v69, v69
	v_fmac_f32_e32 v78, v80, v80
	v_fmac_f32_e32 v74, v76, v76
	v_fmac_f32_e32 v70, v72, v72
	v_fmac_f32_e32 v66, v68, v68
	v_add_f32_e32 v78, v79, v78
	v_add_f32_e32 v74, v75, v74
	v_add_f32_e32 v70, v71, v70
	v_add_f32_e32 v66, v67, v66
	v_add_f32_e32 v74, v78, v74
	v_add_f32_e32 v66, v70, v66
	v_add_f32_e32 v66, v74, v66
	ds_bpermute_b32 v67, v122, v66
	s_waitcnt lgkmcnt(0)
	v_add_f32_e32 v106, v66, v67
	v_add_u32_e32 v66, 0x80, v168
	v_ashrrev_i32_e32 v67, 31, v66
	v_lshlrev_b64 v[66:67], 11, v[66:67]
	v_lshl_add_u64 v[66:67], s[64:65], 0, v[66:67]
	v_lshl_add_u64 v[100:101], v[66:67], 0, v[170:171]
	v_add_u32_e32 v66, 0x90, v168
	v_ashrrev_i32_e32 v67, 31, v66
	v_lshlrev_b64 v[66:67], 11, v[66:67]
	v_lshl_add_u64 v[66:67], s[64:65], 0, v[66:67]
	v_lshl_add_u64 v[98:99], v[66:67], 0, v[170:171]
	v_add_u32_e32 v66, 0xa0, v168
	v_ashrrev_i32_e32 v67, 31, v66
	v_lshlrev_b64 v[66:67], 11, v[66:67]
	v_lshl_add_u64 v[66:67], s[64:65], 0, v[66:67]
	v_lshl_add_u64 v[96:97], v[66:67], 0, v[170:171]
	v_add_u32_e32 v66, 0xb0, v168
	v_ashrrev_i32_e32 v67, 31, v66
	v_lshlrev_b64 v[66:67], 11, v[66:67]
	v_lshl_add_u64 v[66:67], s[64:65], 0, v[66:67]
	v_lshl_add_u64 v[94:95], v[66:67], 0, v[170:171]
	v_lshl_add_u64 v[100:101], v[100:101], 0, v[240:241]
	global_load_dwordx4 v[108:111], v[100:101], off
	global_load_dwordx4 v[90:93], v[100:101], off offset:256
	v_lshl_add_u64 v[98:99], v[98:99], 0, v[240:241]
	global_load_dwordx4 v[86:89], v[98:99], off
	global_load_dwordx4 v[82:85], v[98:99], off offset:256
	v_lshl_add_u64 v[96:97], v[96:97], 0, v[240:241]
	global_load_dwordx4 v[78:81], v[96:97], off
	global_load_dwordx4 v[74:77], v[96:97], off offset:256
	v_lshl_add_u64 v[94:95], v[94:95], 0, v[240:241]
	global_load_dwordx4 v[70:73], v[94:95], off
	global_load_dwordx4 v[66:69], v[94:95], off offset:256
	ds_bpermute_b32 v107, v116, v106
	s_waitcnt vmcnt(7)
	ds_bpermute_b32 v108, v244, v108
	ds_bpermute_b32 v109, v244, v109
	ds_bpermute_b32 v110, v244, v110
	ds_bpermute_b32 v111, v244, v111
	s_waitcnt lgkmcnt(0)
	v_lshlrev_b32_e32 v112, 16, v108
	v_and_b32_e32 v113, 0xffff0000, v108
	v_lshlrev_b32_e32 v108, 16, v109
	v_and_b32_e32 v109, 0xffff0000, v109
	v_pk_add_f32 v[64:65], v[64:65], v[108:109]
	v_lshlrev_b32_e32 v108, 16, v110
	v_and_b32_e32 v109, 0xffff0000, v110
	v_lshlrev_b32_e32 v110, 16, v111
	v_and_b32_e32 v111, 0xffff0000, v111
	v_pk_add_f32 v[62:63], v[62:63], v[112:113]
	v_pk_add_f32 v[60:61], v[60:61], v[110:111]
	s_and_b64 vcc, exec, s[42:43]
	v_pk_add_f32 v[58:59], v[58:59], v[108:109]
	s_cbranch_vccnz .LBB0_744
	v_cvt_pk_bf16_f32 v108, v62, v63
	v_cvt_pk_bf16_f32 v109, v64, v65
	v_cvt_pk_bf16_f32 v110, v58, v59
	v_cvt_pk_bf16_f32 v111, v60, v61
	ds_bpermute_b32 v108, v242, v108
	ds_bpermute_b32 v109, v242, v109
	ds_bpermute_b32 v110, v242, v110
	ds_bpermute_b32 v111, v242, v111
	s_waitcnt lgkmcnt(0)
	global_store_dwordx4 v[100:101], v[108:111], off
.LBB0_744:
	s_waitcnt vmcnt(6)
	ds_bpermute_b32 v90, v244, v90
	ds_bpermute_b32 v91, v244, v91
	ds_bpermute_b32 v92, v244, v92
	ds_bpermute_b32 v93, v244, v93
	s_waitcnt lgkmcnt(0)
	s_nop 0
	v_lshlrev_b32_e32 v108, 16, v90
	v_and_b32_e32 v109, 0xffff0000, v90
	v_lshlrev_b32_e32 v90, 16, v91
	v_and_b32_e32 v91, 0xffff0000, v91
	v_pk_add_f32 v[56:57], v[56:57], v[90:91]
	v_lshlrev_b32_e32 v90, 16, v92
	v_and_b32_e32 v91, 0xffff0000, v92
	v_lshlrev_b32_e32 v92, 16, v93
	v_and_b32_e32 v93, 0xffff0000, v93
	v_pk_add_f32 v[54:55], v[54:55], v[108:109]
	v_pk_add_f32 v[52:53], v[52:53], v[92:93]
	s_and_b64 vcc, exec, s[42:43]
	v_pk_add_f32 v[50:51], v[50:51], v[90:91]
	s_cbranch_vccnz .LBB0_746
	v_cvt_pk_bf16_f32 v90, v54, v55
	v_cvt_pk_bf16_f32 v91, v56, v57
	v_cvt_pk_bf16_f32 v92, v50, v51
	v_cvt_pk_bf16_f32 v93, v52, v53
	ds_bpermute_b32 v90, v242, v90
	ds_bpermute_b32 v91, v242, v91
	ds_bpermute_b32 v92, v242, v92
	ds_bpermute_b32 v93, v242, v93
	s_waitcnt lgkmcnt(0)
	global_store_dwordx4 v[100:101], v[90:93], off offset:256
.LBB0_746:
	v_mul_f32_e32 v63, v63, v63
	v_mul_f32_e32 v59, v59, v59
	v_mul_f32_e32 v55, v55, v55
	v_mul_f32_e32 v51, v51, v51
	v_fmac_f32_e32 v63, v62, v62
	v_mul_f32_e32 v62, v65, v65
	v_fmac_f32_e32 v59, v58, v58
	v_mul_f32_e32 v58, v61, v61
	v_fmac_f32_e32 v55, v54, v54
	v_mul_f32_e32 v54, v57, v57
	v_fmac_f32_e32 v51, v50, v50
	v_mul_f32_e32 v50, v53, v53
	v_fmac_f32_e32 v62, v64, v64
	v_fmac_f32_e32 v58, v60, v60
	v_fmac_f32_e32 v54, v56, v56
	v_fmac_f32_e32 v50, v52, v52
	v_add_f32_e32 v62, v63, v62
	v_add_f32_e32 v58, v59, v58
	v_add_f32_e32 v54, v55, v54
	v_add_f32_e32 v50, v51, v50
	v_add_f32_e32 v58, v62, v58
	v_add_f32_e32 v50, v54, v50
	v_add_f32_e32 v50, v58, v50
	ds_bpermute_b32 v51, v122, v50
	s_waitcnt vmcnt(5)
	ds_bpermute_b32 v86, v244, v86
	ds_bpermute_b32 v87, v244, v87
	ds_bpermute_b32 v88, v244, v88
	ds_bpermute_b32 v89, v244, v89
	s_waitcnt lgkmcnt(0)
	v_lshlrev_b32_e32 v52, 16, v86
	v_and_b32_e32 v53, 0xffff0000, v86
	v_lshlrev_b32_e32 v54, 16, v87
	v_and_b32_e32 v55, 0xffff0000, v87
	s_waitcnt lgkmcnt(0)
	v_add_f32_e32 v50, v50, v51
	ds_bpermute_b32 v51, v116, v50
	v_pk_add_f32 v[48:49], v[48:49], v[54:55]
	v_pk_add_f32 v[46:47], v[46:47], v[52:53]
	v_lshlrev_b32_e32 v52, 16, v88
	v_and_b32_e32 v53, 0xffff0000, v88
	v_lshlrev_b32_e32 v54, 16, v89
	v_and_b32_e32 v55, 0xffff0000, v89
	v_pk_add_f32 v[44:45], v[44:45], v[54:55]
	s_and_b64 vcc, exec, s[42:43]
	v_pk_add_f32 v[42:43], v[42:43], v[52:53]
	s_cbranch_vccnz .LBB0_748
	v_cvt_pk_bf16_f32 v52, v46, v47
	v_cvt_pk_bf16_f32 v53, v48, v49
	v_cvt_pk_bf16_f32 v54, v42, v43
	v_cvt_pk_bf16_f32 v55, v44, v45
	ds_bpermute_b32 v52, v242, v52
	ds_bpermute_b32 v53, v242, v53
	ds_bpermute_b32 v54, v242, v54
	ds_bpermute_b32 v55, v242, v55
	s_waitcnt lgkmcnt(0)
	global_store_dwordx4 v[98:99], v[52:55], off
.LBB0_748:
	s_waitcnt vmcnt(4)
	ds_bpermute_b32 v82, v244, v82
	ds_bpermute_b32 v83, v244, v83
	ds_bpermute_b32 v84, v244, v84
	ds_bpermute_b32 v85, v244, v85
	s_waitcnt lgkmcnt(0)
	s_nop 0
	v_lshlrev_b32_e32 v52, 16, v82
	v_and_b32_e32 v53, 0xffff0000, v82
	v_lshlrev_b32_e32 v54, 16, v83
	v_and_b32_e32 v55, 0xffff0000, v83
	v_pk_add_f32 v[40:41], v[40:41], v[54:55]
	v_pk_add_f32 v[38:39], v[38:39], v[52:53]
	v_lshlrev_b32_e32 v52, 16, v84
	v_and_b32_e32 v53, 0xffff0000, v84
	v_lshlrev_b32_e32 v54, 16, v85
	v_and_b32_e32 v55, 0xffff0000, v85
	v_pk_add_f32 v[36:37], v[36:37], v[54:55]
	s_and_b64 vcc, exec, s[42:43]
	v_pk_add_f32 v[34:35], v[34:35], v[52:53]
	s_cbranch_vccnz .LBB0_750
	v_cvt_pk_bf16_f32 v52, v38, v39
	v_cvt_pk_bf16_f32 v53, v40, v41
	v_cvt_pk_bf16_f32 v54, v34, v35
	v_cvt_pk_bf16_f32 v55, v36, v37
	ds_bpermute_b32 v52, v242, v52
	ds_bpermute_b32 v53, v242, v53
	ds_bpermute_b32 v54, v242, v54
	ds_bpermute_b32 v55, v242, v55
	s_waitcnt lgkmcnt(0)
	global_store_dwordx4 v[98:99], v[52:55], off offset:256
.LBB0_750:
	v_mul_f32_e32 v47, v47, v47
	v_mul_f32_e32 v43, v43, v43
	v_mul_f32_e32 v39, v39, v39
	v_mul_f32_e32 v35, v35, v35
	v_fmac_f32_e32 v47, v46, v46
	v_mul_f32_e32 v46, v49, v49
	v_fmac_f32_e32 v43, v42, v42
	v_mul_f32_e32 v42, v45, v45
	v_fmac_f32_e32 v39, v38, v38
	v_mul_f32_e32 v38, v41, v41
	v_fmac_f32_e32 v35, v34, v34
	v_mul_f32_e32 v34, v37, v37
	v_fmac_f32_e32 v46, v48, v48
	v_fmac_f32_e32 v42, v44, v44
	v_fmac_f32_e32 v38, v40, v40
	v_fmac_f32_e32 v34, v36, v36
	v_add_f32_e32 v46, v47, v46
	v_add_f32_e32 v42, v43, v42
	v_add_f32_e32 v38, v39, v38
	v_add_f32_e32 v34, v35, v34
	v_add_f32_e32 v42, v46, v42
	v_add_f32_e32 v34, v38, v34
	v_add_f32_e32 v34, v42, v34
	ds_bpermute_b32 v35, v122, v34
	s_waitcnt vmcnt(3)
	ds_bpermute_b32 v78, v244, v78
	ds_bpermute_b32 v79, v244, v79
	ds_bpermute_b32 v80, v244, v80
	ds_bpermute_b32 v81, v244, v81
	s_waitcnt lgkmcnt(0)
	v_lshlrev_b32_e32 v36, 16, v78
	v_and_b32_e32 v37, 0xffff0000, v78
	v_lshlrev_b32_e32 v38, 16, v79
	v_and_b32_e32 v39, 0xffff0000, v79
	s_waitcnt lgkmcnt(0)
	v_add_f32_e32 v34, v34, v35
	ds_bpermute_b32 v35, v116, v34
	v_pk_add_f32 v[32:33], v[32:33], v[38:39]
	v_pk_add_f32 v[30:31], v[30:31], v[36:37]
	v_lshlrev_b32_e32 v36, 16, v80
	v_and_b32_e32 v37, 0xffff0000, v80
	v_lshlrev_b32_e32 v38, 16, v81
	v_and_b32_e32 v39, 0xffff0000, v81
	v_pk_add_f32 v[28:29], v[28:29], v[38:39]
	s_and_b64 vcc, exec, s[42:43]
	v_pk_add_f32 v[26:27], v[26:27], v[36:37]
	s_cbranch_vccnz .LBB0_752
	v_cvt_pk_bf16_f32 v36, v30, v31
	v_cvt_pk_bf16_f32 v37, v32, v33
	v_cvt_pk_bf16_f32 v38, v26, v27
	v_cvt_pk_bf16_f32 v39, v28, v29
	ds_bpermute_b32 v36, v242, v36
	ds_bpermute_b32 v37, v242, v37
	ds_bpermute_b32 v38, v242, v38
	ds_bpermute_b32 v39, v242, v39
	s_waitcnt lgkmcnt(0)
	global_store_dwordx4 v[96:97], v[36:39], off
.LBB0_752:
	s_waitcnt vmcnt(2)
	ds_bpermute_b32 v74, v244, v74
	ds_bpermute_b32 v75, v244, v75
	ds_bpermute_b32 v76, v244, v76
	ds_bpermute_b32 v77, v244, v77
	s_waitcnt lgkmcnt(0)
	s_nop 0
	v_lshlrev_b32_e32 v36, 16, v74
	v_and_b32_e32 v37, 0xffff0000, v74
	v_lshlrev_b32_e32 v38, 16, v75
	v_and_b32_e32 v39, 0xffff0000, v75
	v_pk_add_f32 v[24:25], v[24:25], v[38:39]
	v_pk_add_f32 v[22:23], v[22:23], v[36:37]
	v_lshlrev_b32_e32 v36, 16, v76
	v_and_b32_e32 v37, 0xffff0000, v76
	v_lshlrev_b32_e32 v38, 16, v77
	v_and_b32_e32 v39, 0xffff0000, v77
	v_pk_add_f32 v[20:21], v[20:21], v[38:39]
	s_and_b64 vcc, exec, s[42:43]
	v_pk_add_f32 v[18:19], v[18:19], v[36:37]
	s_cbranch_vccnz .LBB0_754
	v_cvt_pk_bf16_f32 v36, v22, v23
	v_cvt_pk_bf16_f32 v37, v24, v25
	v_cvt_pk_bf16_f32 v38, v18, v19
	v_cvt_pk_bf16_f32 v39, v20, v21
	ds_bpermute_b32 v36, v242, v36
	ds_bpermute_b32 v37, v242, v37
	ds_bpermute_b32 v38, v242, v38
	ds_bpermute_b32 v39, v242, v39
	s_waitcnt lgkmcnt(0)
	global_store_dwordx4 v[96:97], v[36:39], off offset:256
.LBB0_754:
	v_mul_f32_e32 v31, v31, v31
	v_mul_f32_e32 v27, v27, v27
	v_mul_f32_e32 v23, v23, v23
	v_mul_f32_e32 v19, v19, v19
	v_fmac_f32_e32 v31, v30, v30
	v_mul_f32_e32 v30, v33, v33
	v_fmac_f32_e32 v27, v26, v26
	v_mul_f32_e32 v26, v29, v29
	v_fmac_f32_e32 v23, v22, v22
	v_mul_f32_e32 v22, v25, v25
	v_fmac_f32_e32 v19, v18, v18
	v_mul_f32_e32 v18, v21, v21
	v_fmac_f32_e32 v30, v32, v32
	v_fmac_f32_e32 v26, v28, v28
	v_fmac_f32_e32 v22, v24, v24
	v_fmac_f32_e32 v18, v20, v20
	v_add_f32_e32 v30, v31, v30
	v_add_f32_e32 v26, v27, v26
	v_add_f32_e32 v22, v23, v22
	v_add_f32_e32 v18, v19, v18
	v_add_f32_e32 v26, v30, v26
	v_add_f32_e32 v18, v22, v18
	v_add_f32_e32 v18, v26, v18
	ds_bpermute_b32 v19, v122, v18
	s_waitcnt vmcnt(1)
	ds_bpermute_b32 v70, v244, v70
	ds_bpermute_b32 v71, v244, v71
	ds_bpermute_b32 v72, v244, v72
	ds_bpermute_b32 v73, v244, v73
	s_waitcnt lgkmcnt(0)
	v_lshlrev_b32_e32 v20, 16, v70
	v_and_b32_e32 v21, 0xffff0000, v70
	v_lshlrev_b32_e32 v22, 16, v71
	v_and_b32_e32 v23, 0xffff0000, v71
	s_waitcnt lgkmcnt(0)
	v_add_f32_e32 v18, v18, v19
	ds_bpermute_b32 v19, v116, v18
	v_pk_add_f32 v[16:17], v[16:17], v[22:23]
	v_pk_add_f32 v[14:15], v[14:15], v[20:21]
	v_lshlrev_b32_e32 v20, 16, v72
	v_and_b32_e32 v21, 0xffff0000, v72
	v_lshlrev_b32_e32 v22, 16, v73
	v_and_b32_e32 v23, 0xffff0000, v73
	v_pk_add_f32 v[12:13], v[12:13], v[22:23]
	s_and_b64 vcc, exec, s[42:43]
	v_pk_add_f32 v[10:11], v[10:11], v[20:21]
	s_cbranch_vccnz .LBB0_756
	v_cvt_pk_bf16_f32 v20, v14, v15
	v_cvt_pk_bf16_f32 v21, v16, v17
	v_cvt_pk_bf16_f32 v22, v10, v11
	v_cvt_pk_bf16_f32 v23, v12, v13
	ds_bpermute_b32 v20, v242, v20
	ds_bpermute_b32 v21, v242, v21
	ds_bpermute_b32 v22, v242, v22
	ds_bpermute_b32 v23, v242, v23
	s_waitcnt lgkmcnt(0)
	global_store_dwordx4 v[94:95], v[20:23], off
.LBB0_756:
	s_waitcnt vmcnt(0)
	ds_bpermute_b32 v66, v244, v66
	ds_bpermute_b32 v67, v244, v67
	ds_bpermute_b32 v68, v244, v68
	ds_bpermute_b32 v69, v244, v69
	s_waitcnt lgkmcnt(0)
	s_nop 0
	v_lshlrev_b32_e32 v20, 16, v66
	v_and_b32_e32 v21, 0xffff0000, v66
	v_lshlrev_b32_e32 v22, 16, v67
	v_and_b32_e32 v23, 0xffff0000, v67
	v_pk_add_f32 v[8:9], v[8:9], v[22:23]
	v_pk_add_f32 v[6:7], v[6:7], v[20:21]
	v_lshlrev_b32_e32 v20, 16, v68
	v_and_b32_e32 v21, 0xffff0000, v68
	v_lshlrev_b32_e32 v22, 16, v69
	v_and_b32_e32 v23, 0xffff0000, v69
	v_pk_add_f32 v[4:5], v[4:5], v[22:23]
	s_and_b64 vcc, exec, s[42:43]
	v_pk_add_f32 v[2:3], v[2:3], v[20:21]
	s_cbranch_vccnz .LBB0_758
	v_cvt_pk_bf16_f32 v20, v6, v7
	v_cvt_pk_bf16_f32 v21, v8, v9
	v_cvt_pk_bf16_f32 v22, v2, v3
	v_cvt_pk_bf16_f32 v23, v4, v5
	ds_bpermute_b32 v20, v242, v20
	ds_bpermute_b32 v21, v242, v21
	ds_bpermute_b32 v22, v242, v22
	ds_bpermute_b32 v23, v242, v23
	s_waitcnt lgkmcnt(0)
	global_store_dwordx4 v[94:95], v[20:23], off offset:256
